# grid barrier: non-leader workgroups spin on the top-level generation word directly instead of waiting for their XCD leader to re-publish it (one atomic and one poll round less on the release path)
# speedup vs baseline: 1.0043x; 1.0007x over previous
.LBB0_110:
	s_lshl_b32 s74, s41, 8
	v_lshl_add_u64 v[4:5], v[2:3], 0, s[74:75]
	v_add_co_u32_e32 v8, vcc, 0x1eb8a000, v4
	s_mov_b64 s[4:5], 0x1eb89000
	s_nop 0
	v_addc_co_u32_e32 v9, vcc, 0, v5, vcc
	global_atomic_add v7, v[8:9], v246, off offset:1024 sc0
	v_cvt_f32_u32_e32 v8, v6
	v_sub_u32_e32 v9, 0, v6
	v_lshl_add_u64 v[4:5], v[4:5], 0, s[4:5]
	v_rcp_iflag_f32_e32 v8, v8
	s_nop 0
	v_mul_f32_e32 v8, 0x4f7ffffe, v8
	v_cvt_u32_f32_e32 v8, v8
	v_mul_lo_u32 v9, v9, v8
	v_mul_hi_u32 v9, v8, v9
	v_add_u32_e32 v8, v8, v9
	s_waitcnt vmcnt(0) lgkmcnt(0)
	v_mul_hi_u32 v8, v7, v8
	v_mul_lo_u32 v9, v8, v6
	v_add_u32_e32 v10, 1, v7
	v_sub_u32_e32 v7, v7, v9
	v_add_u32_e32 v11, 1, v8
	v_cmp_ge_u32_e32 vcc, v7, v6
	v_sub_u32_e32 v9, v7, v6
	s_nop 0
	v_cndmask_b32_e32 v8, v8, v11, vcc
	v_cndmask_b32_e32 v7, v7, v9, vcc
	v_add_u32_e32 v9, 1, v8
	v_cmp_ge_u32_e32 vcc, v7, v6
	s_nop 1
	v_cndmask_b32_e32 v7, v8, v9, vcc
	v_mad_u64_u32 v[8:9], s[4:5], v6, v7, v[6:7]
	v_cmp_ne_u32_e32 vcc, v10, v8
	s_and_saveexec_b64 s[4:5], vcc
	s_xor_b64 s[4:5], exec, s[4:5]
	v_readlane_b32 s41, v255, 12
	s_cbranch_execz .LBB0_123
	v_add_co_u32_e32 v8, vcc, 0x1eb8c100, v2
	s_nop 1
	v_addc_co_u32_e32 v9, vcc, 0, v3, vcc
	global_load_dword v0, v[8:9], off offset:1024 sc1
	s_waitcnt vmcnt(0) lgkmcnt(0)
	v_cmp_eq_u32_e32 vcc, v0, v7
	s_and_saveexec_b64 s[6:7], vcc
	s_cbranch_execz .LBB0_122
	s_mov_b64 s[8:9], 0x1eb8c500
	v_lshl_add_u64 v[4:5], v[2:3], 0, s[8:9]
	s_mov_b64 s[8:9], 0x1eb89200
	v_lshl_add_u64 v[2:3], v[2:3], 0, s[8:9]
	s_mov_b32 s22, 1
	s_mov_b64 s[8:9], 0
	s_branch .LBB0_114

.LBB0_374:
	s_lshl_b32 s74, s36, 8
	v_lshl_add_u64 v[4:5], v[2:3], 0, s[74:75]
	v_add_co_u32_e32 v8, vcc, 0x1eb8a000, v4
	s_mov_b64 s[4:5], 0x1eb89000
	s_nop 0
	v_addc_co_u32_e32 v9, vcc, 0, v5, vcc
	global_atomic_add v7, v[8:9], v246, off offset:1024 sc0
	v_cvt_f32_u32_e32 v8, v6
	v_sub_u32_e32 v9, 0, v6
	v_lshl_add_u64 v[4:5], v[4:5], 0, s[4:5]
	v_rcp_iflag_f32_e32 v8, v8
	s_nop 0
	v_mul_f32_e32 v8, 0x4f7ffffe, v8
	v_cvt_u32_f32_e32 v8, v8
	v_mul_lo_u32 v9, v9, v8
	v_mul_hi_u32 v9, v8, v9
	v_add_u32_e32 v8, v8, v9
	s_waitcnt vmcnt(0) lgkmcnt(0)
	v_mul_hi_u32 v8, v7, v8
	v_mul_lo_u32 v9, v8, v6
	v_add_u32_e32 v10, 1, v7
	v_sub_u32_e32 v7, v7, v9
	v_add_u32_e32 v11, 1, v8
	v_cmp_ge_u32_e32 vcc, v7, v6
	v_sub_u32_e32 v9, v7, v6
	s_nop 0
	v_cndmask_b32_e32 v8, v8, v11, vcc
	v_cndmask_b32_e32 v7, v7, v9, vcc
	v_add_u32_e32 v9, 1, v8
	v_cmp_ge_u32_e32 vcc, v7, v6
	s_nop 1
	v_cndmask_b32_e32 v7, v8, v9, vcc
	v_mad_u64_u32 v[8:9], s[4:5], v6, v7, v[6:7]
	v_cmp_ne_u32_e32 vcc, v10, v8
	s_and_saveexec_b64 s[4:5], vcc
	s_xor_b64 s[4:5], exec, s[4:5]
	s_cbranch_execz .LBB0_387
	v_add_co_u32_e32 v8, vcc, 0x1eb8c100, v2
	s_nop 1
	v_addc_co_u32_e32 v9, vcc, 0, v3, vcc
	global_load_dword v0, v[8:9], off offset:1024 sc1
	s_waitcnt vmcnt(0) lgkmcnt(0)
	v_cmp_eq_u32_e32 vcc, v0, v7
	s_and_saveexec_b64 s[6:7], vcc
	s_cbranch_execz .LBB0_386
	s_mov_b64 s[8:9], 0x1eb8c500
	v_lshl_add_u64 v[4:5], v[2:3], 0, s[8:9]
	s_mov_b64 s[8:9], 0x1eb89200
	v_lshl_add_u64 v[2:3], v[2:3], 0, s[8:9]
	s_mov_b32 s22, 1
	s_mov_b64 s[8:9], 0
	s_branch .LBB0_378

.LBB0_676:
	s_lshl_b32 s74, s37, 8
	v_lshl_add_u64 v[4:5], v[2:3], 0, s[74:75]
	v_add_co_u32_e32 v8, vcc, 0x1eb8a000, v4
	s_mov_b64 s[4:5], 0x1eb89000
	s_nop 0
	v_addc_co_u32_e32 v9, vcc, 0, v5, vcc
	global_atomic_add v7, v[8:9], v246, off offset:1024 sc0
	v_cvt_f32_u32_e32 v8, v6
	v_sub_u32_e32 v9, 0, v6
	v_lshl_add_u64 v[4:5], v[4:5], 0, s[4:5]
	v_rcp_iflag_f32_e32 v8, v8
	s_nop 0
	v_mul_f32_e32 v8, 0x4f7ffffe, v8
	v_cvt_u32_f32_e32 v8, v8
	v_mul_lo_u32 v9, v9, v8
	v_mul_hi_u32 v9, v8, v9
	v_add_u32_e32 v8, v8, v9
	s_waitcnt vmcnt(0) lgkmcnt(0)
	v_mul_hi_u32 v8, v7, v8
	v_mul_lo_u32 v9, v8, v6
	v_add_u32_e32 v10, 1, v7
	v_sub_u32_e32 v7, v7, v9
	v_add_u32_e32 v11, 1, v8
	v_cmp_ge_u32_e32 vcc, v7, v6
	v_sub_u32_e32 v9, v7, v6
	s_nop 0
	v_cndmask_b32_e32 v8, v8, v11, vcc
	v_cndmask_b32_e32 v7, v7, v9, vcc
	v_add_u32_e32 v9, 1, v8
	v_cmp_ge_u32_e32 vcc, v7, v6
	s_nop 1
	v_cndmask_b32_e32 v7, v8, v9, vcc
	v_mad_u64_u32 v[8:9], s[4:5], v6, v7, v[6:7]
	v_cmp_ne_u32_e32 vcc, v10, v8
	s_and_saveexec_b64 s[4:5], vcc
	s_xor_b64 s[4:5], exec, s[4:5]
	s_cbranch_execz .LBB0_689
	v_add_co_u32_e32 v8, vcc, 0x1eb8c100, v2
	s_nop 1
	v_addc_co_u32_e32 v9, vcc, 0, v3, vcc
	global_load_dword v0, v[8:9], off offset:1024 sc1
	s_waitcnt vmcnt(0) lgkmcnt(0)
	v_cmp_eq_u32_e32 vcc, v0, v7
	s_and_saveexec_b64 s[6:7], vcc
	s_cbranch_execz .LBB0_688
	s_mov_b64 s[8:9], 0x1eb8c500
	v_lshl_add_u64 v[4:5], v[2:3], 0, s[8:9]
	s_mov_b64 s[8:9], 0x1eb89200
	v_lshl_add_u64 v[2:3], v[2:3], 0, s[8:9]
	s_mov_b32 s22, 1
	s_mov_b64 s[8:9], 0
	s_branch .LBB0_680

.LBB0_846:
	s_lshl_b32 s74, s41, 8
	v_lshl_add_u64 v[4:5], v[2:3], 0, s[74:75]
	v_add_co_u32_e32 v8, vcc, 0x1eb8a000, v4
	s_mov_b64 s[4:5], 0x1eb89000
	s_nop 0
	v_addc_co_u32_e32 v9, vcc, 0, v5, vcc
	global_atomic_add v7, v[8:9], v246, off offset:1024 sc0
	v_cvt_f32_u32_e32 v8, v6
	v_sub_u32_e32 v9, 0, v6
	v_lshl_add_u64 v[4:5], v[4:5], 0, s[4:5]
	v_rcp_iflag_f32_e32 v8, v8
	s_nop 0
	v_mul_f32_e32 v8, 0x4f7ffffe, v8
	v_cvt_u32_f32_e32 v8, v8
	v_mul_lo_u32 v9, v9, v8
	v_mul_hi_u32 v9, v8, v9
	v_add_u32_e32 v8, v8, v9
	s_waitcnt vmcnt(0) lgkmcnt(0)
	v_mul_hi_u32 v8, v7, v8
	v_mul_lo_u32 v9, v8, v6
	v_add_u32_e32 v10, 1, v7
	v_sub_u32_e32 v7, v7, v9
	v_add_u32_e32 v11, 1, v8
	v_cmp_ge_u32_e32 vcc, v7, v6
	v_sub_u32_e32 v9, v7, v6
	s_nop 0
	v_cndmask_b32_e32 v8, v8, v11, vcc
	v_cndmask_b32_e32 v7, v7, v9, vcc
	v_add_u32_e32 v9, 1, v8
	v_cmp_ge_u32_e32 vcc, v7, v6
	s_nop 1
	v_cndmask_b32_e32 v7, v8, v9, vcc
	v_mad_u64_u32 v[8:9], s[4:5], v6, v7, v[6:7]
	v_cmp_ne_u32_e32 vcc, v10, v8
	s_and_saveexec_b64 s[4:5], vcc
	s_xor_b64 s[4:5], exec, s[4:5]
	v_readlane_b32 s41, v255, 12
	s_cbranch_execz .LBB0_859
	v_add_co_u32_e32 v8, vcc, 0x1eb8c100, v2
	s_nop 1
	v_addc_co_u32_e32 v9, vcc, 0, v3, vcc
	global_load_dword v0, v[8:9], off offset:1024 sc1
	s_waitcnt vmcnt(0) lgkmcnt(0)
	v_cmp_eq_u32_e32 vcc, v0, v7
	s_and_saveexec_b64 s[6:7], vcc
	s_cbranch_execz .LBB0_858
	s_mov_b64 s[10:11], 0x1eb8c500
	v_lshl_add_u64 v[4:5], v[2:3], 0, s[10:11]
	s_mov_b64 s[10:11], 0x1eb89200
	v_lshl_add_u64 v[2:3], v[2:3], 0, s[10:11]
	s_mov_b32 s24, 1
	s_mov_b64 s[10:11], 0
	s_branch .LBB0_850

.LBB0_1030:
	s_lshl_b32 s74, s41, 8
	v_lshl_add_u64 v[4:5], v[2:3], 0, s[74:75]
	v_add_co_u32_e32 v8, vcc, 0x1eb8a000, v4
	s_mov_b64 s[4:5], 0x1eb89000
	s_nop 0
	v_addc_co_u32_e32 v9, vcc, 0, v5, vcc
	global_atomic_add v7, v[8:9], v246, off offset:1024 sc0
	v_cvt_f32_u32_e32 v8, v6
	v_sub_u32_e32 v9, 0, v6
	v_lshl_add_u64 v[4:5], v[4:5], 0, s[4:5]
	v_rcp_iflag_f32_e32 v8, v8
	s_nop 0
	v_mul_f32_e32 v8, 0x4f7ffffe, v8
	v_cvt_u32_f32_e32 v8, v8
	v_mul_lo_u32 v9, v9, v8
	v_mul_hi_u32 v9, v8, v9
	v_add_u32_e32 v8, v8, v9
	s_waitcnt vmcnt(0) lgkmcnt(0)
	v_mul_hi_u32 v8, v7, v8
	v_mul_lo_u32 v9, v8, v6
	v_add_u32_e32 v10, 1, v7
	v_sub_u32_e32 v7, v7, v9
	v_add_u32_e32 v11, 1, v8
	v_cmp_ge_u32_e32 vcc, v7, v6
	v_sub_u32_e32 v9, v7, v6
	s_nop 0
	v_cndmask_b32_e32 v8, v8, v11, vcc
	v_cndmask_b32_e32 v7, v7, v9, vcc
	v_add_u32_e32 v9, 1, v8
	v_cmp_ge_u32_e32 vcc, v7, v6
	s_nop 1
	v_cndmask_b32_e32 v7, v8, v9, vcc
	v_mad_u64_u32 v[8:9], s[4:5], v6, v7, v[6:7]
	v_cmp_ne_u32_e32 vcc, v10, v8
	s_and_saveexec_b64 s[4:5], vcc
	s_xor_b64 s[4:5], exec, s[4:5]
	s_cbranch_execz .LBB0_1043
	v_add_co_u32_e32 v8, vcc, 0x1eb8c100, v2
	s_nop 1
	v_addc_co_u32_e32 v9, vcc, 0, v3, vcc
	global_load_dword v0, v[8:9], off offset:1024 sc1
	s_waitcnt vmcnt(0) lgkmcnt(0)
	v_cmp_eq_u32_e32 vcc, v0, v7
	s_and_saveexec_b64 s[6:7], vcc
	s_cbranch_execz .LBB0_1042
	s_mov_b64 s[10:11], 0x1eb8c500
	v_lshl_add_u64 v[4:5], v[2:3], 0, s[10:11]
	s_mov_b64 s[10:11], 0x1eb89200
	v_lshl_add_u64 v[2:3], v[2:3], 0, s[10:11]
	s_mov_b32 s24, 1
	s_mov_b64 s[10:11], 0
	s_branch .LBB0_1034
